# kt task inner loops: 8 Bbar loads per 8-state group hoisted and issued together (were waited one by one), on top of v20
# speedup vs baseline: 1.0063x; 1.0063x over previous
; __device__ __forceinline__ void ssm_kt_task(unsigned char* ws, LAS unsigned char* lds, int l, int task, int tid) {
;     ...
;         const float* cr_ = cre + (g * NP + p) * NS; const float* ci_ = cim + (g * NP + p) * NS; const f32x2* bb = bbar + (size_t)((g * 2 + dir) * NS) * NP + q;
; #pragma unroll 8
;         for (int n = 0; n < NS; ++n) { const float cr = cr_[n], ci = ci_[n]; const f32x2 b = bb[n * NP];
;             const float xr = cr * b.x - ci * b.y, xi = cr * b.y + ci * b.x;
; #pragma unroll
;             for (int s = 0; s < 8; ++s) { const f32x2 pw = Pl[(dir * 64 + n) * 16 + half * 8 + s]; acc[s] += xr * pw.x - xi * pw.y; } }
.LBB0_287:
	v_lshl_add_u64 v[4:5], v[34:35], 0, s[50:51]
	v_add_co_u32_e32 v2, vcc, 0xe400000, v4
	v_lshl_add_u64 v[0:1], v[4:5], 0, s[28:29]
	s_nop 0
	v_addc_co_u32_e32 v3, vcc, 0, v5, vcc
	v_lshl_add_u64 v[6:7], v[4:5], 0, s[26:27]
	v_add_co_u32_e32 v4, vcc, 0xe480000, v4
	global_load_dwordx4 v[8:11], v[2:3], off
	s_nop 0
	global_load_dwordx4 v[0:3], v[0:1], off offset:16
	v_addc_co_u32_e32 v5, vcc, 0, v5, vcc
	global_load_dwordx4 v[12:15], v[4:5], off
	s_nop 0
	global_load_dwordx4 v[4:7], v[6:7], off offset:16
	s_nop 0
	global_load_dwordx2 v[100:101], v[36:37], off offset:-512
	global_load_dwordx2 v[102:103], v[36:37], off offset:-384
	global_load_dwordx2 v[104:105], v[36:37], off offset:-256
	global_load_dwordx2 v[106:107], v[36:37], off offset:-128
	global_load_dwordx2 v[108:109], v[36:37], off
	global_load_dwordx2 v[110:111], v[36:37], off offset:128
	global_load_dwordx2 v[112:113], v[36:37], off offset:256
	global_load_dwordx2 v[114:115], v[36:37], off offset:384
	ds_read_b128 v[48:51], v47
	ds_read_b128 v[52:55], v47 offset:16
	ds_read_b128 v[56:59], v47 offset:32
	ds_read_b128 v[60:63], v47 offset:48
	s_add_u32 s50, s50, 32
	s_waitcnt lgkmcnt(3)
	v_mov_b32_e32 v71, v50
	v_mov_b32_e32 v50, v49
	v_mov_b32_e32 v70, v48
	s_addc_u32 s51, s51, 0
	s_cmpk_lg_i32 s50, 0x100
	s_waitcnt vmcnt(0)
	v_pk_mul_f32 v[66:67], v[12:13], v[100:101] op_sel:[0,1] op_sel_hi:[0,0]
	v_pk_fma_f32 v[68:69], v[8:9], v[100:101], v[66:67] op_sel_hi:[0,1,1] neg_lo:[0,0,1] neg_hi:[0,0,1]
	v_pk_fma_f32 v[64:65], v[8:9], v[100:101], v[66:67] op_sel_hi:[0,1,1]
	v_pk_mul_f32 v[48:49], v[64:65], v[50:51] op_sel:[1,0]
	v_mov_b32_e32 v66, v68
	v_pk_fma_f32 v[48:49], v[68:69], v[70:71], v[48:49] op_sel_hi:[0,1,1] neg_lo:[0,0,1] neg_hi:[0,0,1]
	v_pk_add_f32 v[70:71], v[30:31], v[48:49]
	s_waitcnt lgkmcnt(2)
	v_mov_b32_e32 v31, v54
	v_mov_b32_e32 v54, v53
	v_mov_b32_e32 v30, v52
	v_pk_mul_f32 v[48:49], v[64:65], v[54:55] op_sel:[1,0]
	v_mov_b32_e32 v67, v65
	v_pk_fma_f32 v[30:31], v[68:69], v[30:31], v[48:49] op_sel_hi:[0,1,1] neg_lo:[0,0,1] neg_hi:[0,0,1]
	v_pk_add_f32 v[72:73], v[28:29], v[30:31]
	s_waitcnt lgkmcnt(1)
	v_mov_b32_e32 v29, v58
	v_mov_b32_e32 v58, v57
	v_mov_b32_e32 v28, v56
	v_pk_mul_f32 v[30:31], v[64:65], v[58:59] op_sel:[1,0]
	s_nop 0
	v_pk_fma_f32 v[28:29], v[68:69], v[28:29], v[30:31] op_sel_hi:[0,1,1] neg_lo:[0,0,1] neg_hi:[0,0,1]
	v_pk_add_f32 v[56:57], v[26:27], v[28:29]
	s_waitcnt lgkmcnt(0)
	v_pk_mul_f32 v[26:27], v[66:67], v[60:61]
	v_pk_mul_f32 v[28:29], v[66:67], v[62:63]
	v_mov_b32_e32 v30, v26
	v_mov_b32_e32 v31, v28
	v_mov_b32_e32 v28, v27
	v_pk_add_f32 v[26:27], v[30:31], v[28:29] neg_lo:[0,1] neg_hi:[0,1]
	s_waitcnt vmcnt(0)
	v_pk_mul_f32 v[12:13], v[12:13], v[102:103] op_sel:[1,1] op_sel_hi:[1,0]
	v_pk_add_f32 v[58:59], v[24:25], v[26:27]
	ds_read_b128 v[24:27], v47 offset:128
	ds_read_b128 v[28:31], v47 offset:144
	ds_read_b128 v[48:51], v47 offset:160
	ds_read_b128 v[52:55], v47 offset:176
	v_pk_fma_f32 v[62:63], v[8:9], v[102:103], v[12:13] op_sel:[1,0,0] neg_lo:[0,0,1] neg_hi:[0,0,1]
	v_pk_fma_f32 v[8:9], v[8:9], v[102:103], v[12:13] op_sel:[1,0,0]
	s_waitcnt lgkmcnt(3)
	v_mov_b32_e32 v61, v26
	v_mov_b32_e32 v26, v25
	v_mov_b32_e32 v60, v24
	v_pk_mul_f32 v[24:25], v[8:9], v[26:27] op_sel:[1,0]
	v_mov_b32_e32 v13, v9
	v_pk_fma_f32 v[24:25], v[62:63], v[60:61], v[24:25] op_sel_hi:[0,1,1] neg_lo:[0,0,1] neg_hi:[0,0,1]
	v_pk_add_f32 v[60:61], v[70:71], v[24:25]
	s_waitcnt lgkmcnt(2)
	v_mov_b32_e32 v25, v30
	v_mov_b32_e32 v30, v29
	v_mov_b32_e32 v24, v28
	v_pk_mul_f32 v[26:27], v[8:9], v[30:31] op_sel:[1,0]
	v_mov_b32_e32 v12, v62
	v_pk_fma_f32 v[24:25], v[62:63], v[24:25], v[26:27] op_sel_hi:[0,1,1] neg_lo:[0,0,1] neg_hi:[0,0,1]
	v_pk_add_f32 v[64:65], v[72:73], v[24:25]
	s_waitcnt lgkmcnt(1)
	v_mov_b32_e32 v25, v50
	v_mov_b32_e32 v50, v49
	v_mov_b32_e32 v24, v48
	v_pk_mul_f32 v[8:9], v[8:9], v[50:51] op_sel:[1,0]
	s_nop 0
	v_pk_fma_f32 v[8:9], v[62:63], v[24:25], v[8:9] op_sel_hi:[0,1,1] neg_lo:[0,0,1] neg_hi:[0,0,1]
	v_pk_add_f32 v[8:9], v[56:57], v[8:9]
	s_waitcnt lgkmcnt(0)
	v_pk_mul_f32 v[24:25], v[12:13], v[52:53]
	v_pk_mul_f32 v[12:13], v[12:13], v[54:55]
	v_mov_b32_e32 v26, v24
	v_mov_b32_e32 v27, v12
	v_mov_b32_e32 v12, v25
	v_pk_add_f32 v[12:13], v[26:27], v[12:13] neg_lo:[0,1] neg_hi:[0,1]
	ds_read_b128 v[24:27], v47 offset:256
	ds_read_b128 v[28:31], v47 offset:272
	ds_read_b128 v[48:51], v47 offset:288
	ds_read_b128 v[52:55], v47 offset:304
	v_pk_add_f32 v[12:13], v[58:59], v[12:13]
	s_waitcnt lgkmcnt(3)
	v_mov_b32_e32 v67, v26
	v_mov_b32_e32 v26, v25
	v_mov_b32_e32 v66, v24
	s_waitcnt vmcnt(0)
	v_pk_mul_f32 v[58:59], v[14:15], v[104:105] op_sel:[0,1] op_sel_hi:[0,0]
	v_pk_fma_f32 v[62:63], v[10:11], v[104:105], v[58:59] op_sel_hi:[0,1,1] neg_lo:[0,0,1] neg_hi:[0,0,1]
	v_pk_fma_f32 v[56:57], v[10:11], v[104:105], v[58:59] op_sel_hi:[0,1,1]
	v_pk_mul_f32 v[24:25], v[56:57], v[26:27] op_sel:[1,0]
	v_mov_b32_e32 v59, v57
	v_pk_fma_f32 v[24:25], v[62:63], v[66:67], v[24:25] op_sel_hi:[0,1,1] neg_lo:[0,0,1] neg_hi:[0,0,1]
	v_pk_add_f32 v[60:61], v[60:61], v[24:25]
	s_waitcnt lgkmcnt(2)
	v_mov_b32_e32 v25, v30
	v_mov_b32_e32 v30, v29
	v_mov_b32_e32 v24, v28
	v_pk_mul_f32 v[26:27], v[56:57], v[30:31] op_sel:[1,0]
	v_mov_b32_e32 v58, v62
	v_pk_fma_f32 v[24:25], v[62:63], v[24:25], v[26:27] op_sel_hi:[0,1,1] neg_lo:[0,0,1] neg_hi:[0,0,1]
	v_pk_add_f32 v[64:65], v[64:65], v[24:25]
	s_waitcnt lgkmcnt(1)
	v_mov_b32_e32 v25, v50
	v_mov_b32_e32 v50, v49
	v_pk_mul_f32 v[26:27], v[56:57], v[50:51] op_sel:[1,0]
	v_mov_b32_e32 v24, v48
	v_pk_fma_f32 v[24:25], v[62:63], v[24:25], v[26:27] op_sel_hi:[0,1,1] neg_lo:[0,0,1] neg_hi:[0,0,1]
	v_pk_add_f32 v[8:9], v[8:9], v[24:25]
	s_waitcnt lgkmcnt(0)
; __device__ __forceinline__ void ssm_kt_task(unsigned char* ws, LAS unsigned char* lds, int l, int task, int tid) {
;     ...
;         const float* cr_ = cre + (g * NP + p) * NS; const float* ci_ = cim + (g * NP + p) * NS; const f32x2* bb = bbar + (size_t)((g * 2 + dir) * NS) * NP + q;
; #pragma unroll 8
;         for (int n = 0; n < NS; ++n) { const float cr = cr_[n], ci = ci_[n]; const f32x2 b = bb[n * NP];
;             const float xr = cr * b.x - ci * b.y, xi = cr * b.y + ci * b.x;
; #pragma unroll
;             for (int s = 0; s < 8; ++s) { const f32x2 pw = Pl[(dir * 64 + n) * 16 + half * 8 + s]; acc[s] += xr * pw.x - xi * pw.y; } }
	v_pk_mul_f32 v[24:25], v[58:59], v[52:53]
	v_pk_mul_f32 v[26:27], v[58:59], v[54:55]
	v_mov_b32_e32 v28, v24
	v_mov_b32_e32 v29, v26
	v_mov_b32_e32 v26, v25
	v_pk_add_f32 v[24:25], v[28:29], v[26:27] neg_lo:[0,1] neg_hi:[0,1]
	v_mov_b32_e32 v14, v15
	v_pk_add_f32 v[12:13], v[12:13], v[24:25]
	ds_read_b128 v[24:27], v47 offset:384
	ds_read_b128 v[28:31], v47 offset:400
	ds_read_b128 v[48:51], v47 offset:416
	ds_read_b128 v[52:55], v47 offset:432
	v_mov_b32_e32 v10, v11
	s_waitcnt vmcnt(0)
	v_pk_mul_f32 v[14:15], v[14:15], v[106:107] op_sel:[0,1] op_sel_hi:[0,0]
	v_pk_fma_f32 v[58:59], v[10:11], v[106:107], v[14:15] op_sel_hi:[0,1,1] neg_lo:[0,0,1] neg_hi:[0,0,1]
	v_pk_fma_f32 v[10:11], v[10:11], v[106:107], v[14:15] op_sel_hi:[0,1,1]
	s_waitcnt lgkmcnt(3)
	v_mov_b32_e32 v57, v26
	v_mov_b32_e32 v26, v25
	v_mov_b32_e32 v56, v24
	v_pk_mul_f32 v[24:25], v[10:11], v[26:27] op_sel:[1,0]
	v_mov_b32_e32 v15, v11
	v_pk_fma_f32 v[24:25], v[58:59], v[56:57], v[24:25] op_sel_hi:[0,1,1] neg_lo:[0,0,1] neg_hi:[0,0,1]
	v_pk_add_f32 v[56:57], v[60:61], v[24:25]
	s_waitcnt lgkmcnt(2)
	v_mov_b32_e32 v25, v30
	v_mov_b32_e32 v30, v29
	v_mov_b32_e32 v24, v28
	v_pk_mul_f32 v[26:27], v[10:11], v[30:31] op_sel:[1,0]
	v_mov_b32_e32 v14, v58
	v_pk_fma_f32 v[24:25], v[58:59], v[24:25], v[26:27] op_sel_hi:[0,1,1] neg_lo:[0,0,1] neg_hi:[0,0,1]
	v_pk_add_f32 v[60:61], v[64:65], v[24:25]
	s_waitcnt lgkmcnt(1)
	v_mov_b32_e32 v25, v50
	v_mov_b32_e32 v50, v49
	v_mov_b32_e32 v24, v48
	v_pk_mul_f32 v[10:11], v[10:11], v[50:51] op_sel:[1,0]
	s_nop 0
	v_pk_fma_f32 v[10:11], v[58:59], v[24:25], v[10:11] op_sel_hi:[0,1,1] neg_lo:[0,0,1] neg_hi:[0,0,1]
	v_pk_add_f32 v[48:49], v[8:9], v[10:11]
	s_waitcnt lgkmcnt(0)
	v_pk_mul_f32 v[8:9], v[14:15], v[52:53]
	v_pk_mul_f32 v[10:11], v[14:15], v[54:55]
	v_mov_b32_e32 v14, v8
	v_mov_b32_e32 v15, v10
	v_mov_b32_e32 v10, v9
	v_pk_add_f32 v[8:9], v[14:15], v[10:11] neg_lo:[0,1] neg_hi:[0,1]
	s_waitcnt vmcnt(0)
	v_pk_mul_f32 v[54:55], v[4:5], v[108:109] op_sel:[0,1] op_sel_hi:[0,0]
	v_pk_add_f32 v[50:51], v[12:13], v[8:9]
	ds_read_b128 v[8:11], v47 offset:512
	ds_read_b128 v[12:15], v47 offset:528
	ds_read_b128 v[24:27], v47 offset:544
	ds_read_b128 v[28:31], v47 offset:560
	v_pk_fma_f32 v[58:59], v[0:1], v[108:109], v[54:55] op_sel_hi:[0,1,1] neg_lo:[0,0,1] neg_hi:[0,0,1]
	v_pk_fma_f32 v[52:53], v[0:1], v[108:109], v[54:55] op_sel_hi:[0,1,1]
	s_waitcnt lgkmcnt(3)
	v_mov_b32_e32 v63, v10
	v_mov_b32_e32 v10, v9
	v_mov_b32_e32 v62, v8
	v_pk_mul_f32 v[8:9], v[52:53], v[10:11] op_sel:[1,0]
	v_mov_b32_e32 v55, v53
	v_pk_fma_f32 v[8:9], v[58:59], v[62:63], v[8:9] op_sel_hi:[0,1,1] neg_lo:[0,0,1] neg_hi:[0,0,1]
	v_pk_add_f32 v[56:57], v[56:57], v[8:9]
	s_waitcnt lgkmcnt(2)
	v_mov_b32_e32 v9, v14
	v_mov_b32_e32 v14, v13
	v_mov_b32_e32 v8, v12
	v_pk_mul_f32 v[10:11], v[52:53], v[14:15] op_sel:[1,0]
	v_mov_b32_e32 v54, v58
	v_pk_fma_f32 v[8:9], v[58:59], v[8:9], v[10:11] op_sel_hi:[0,1,1] neg_lo:[0,0,1] neg_hi:[0,0,1]
	v_pk_add_f32 v[60:61], v[60:61], v[8:9]
	s_waitcnt lgkmcnt(1)
	v_mov_b32_e32 v9, v26
	v_mov_b32_e32 v26, v25
	v_pk_mul_f32 v[10:11], v[52:53], v[26:27] op_sel:[1,0]
	v_mov_b32_e32 v8, v24
	v_pk_fma_f32 v[8:9], v[58:59], v[8:9], v[10:11] op_sel_hi:[0,1,1] neg_lo:[0,0,1] neg_hi:[0,0,1]
	v_pk_add_f32 v[48:49], v[48:49], v[8:9]
	s_waitcnt lgkmcnt(0)
	v_pk_mul_f32 v[8:9], v[54:55], v[28:29]
	v_pk_mul_f32 v[10:11], v[54:55], v[30:31]
	v_mov_b32_e32 v12, v8
	v_mov_b32_e32 v13, v10
	v_mov_b32_e32 v10, v9
	v_pk_add_f32 v[8:9], v[12:13], v[10:11] neg_lo:[0,1] neg_hi:[0,1]
	s_waitcnt vmcnt(0)
	v_pk_mul_f32 v[4:5], v[4:5], v[110:111] op_sel:[1,1] op_sel_hi:[1,0]
	v_pk_add_f32 v[50:51], v[50:51], v[8:9]
	ds_read_b128 v[8:11], v47 offset:640
	ds_read_b128 v[12:15], v47 offset:656
	ds_read_b128 v[24:27], v47 offset:672
	ds_read_b128 v[28:31], v47 offset:688
	v_pk_fma_f32 v[54:55], v[0:1], v[110:111], v[4:5] op_sel:[1,0,0] neg_lo:[0,0,1] neg_hi:[0,0,1]
	v_pk_fma_f32 v[0:1], v[0:1], v[110:111], v[4:5] op_sel:[1,0,0]
	s_waitcnt lgkmcnt(3)
	v_mov_b32_e32 v53, v10
	v_mov_b32_e32 v10, v9
	v_mov_b32_e32 v52, v8
	v_pk_mul_f32 v[8:9], v[0:1], v[10:11] op_sel:[1,0]
	v_mov_b32_e32 v5, v1
	v_pk_fma_f32 v[8:9], v[54:55], v[52:53], v[8:9] op_sel_hi:[0,1,1] neg_lo:[0,0,1] neg_hi:[0,0,1]
	v_pk_add_f32 v[52:53], v[56:57], v[8:9]
	s_waitcnt lgkmcnt(2)
; __device__ __forceinline__ void ssm_kt_task(unsigned char* ws, LAS unsigned char* lds, int l, int task, int tid) {
;     ...
;         const float* cr_ = cre + (g * NP + p) * NS; const float* ci_ = cim + (g * NP + p) * NS; const f32x2* bb = bbar + (size_t)((g * 2 + dir) * NS) * NP + q;
; #pragma unroll 8
;         for (int n = 0; n < NS; ++n) { const float cr = cr_[n], ci = ci_[n]; const f32x2 b = bb[n * NP];
;             const float xr = cr * b.x - ci * b.y, xi = cr * b.y + ci * b.x;
; #pragma unroll
;             for (int s = 0; s < 8; ++s) { const f32x2 pw = Pl[(dir * 64 + n) * 16 + half * 8 + s]; acc[s] += xr * pw.x - xi * pw.y; } }
	v_mov_b32_e32 v9, v14
	v_mov_b32_e32 v14, v13
	v_mov_b32_e32 v8, v12
	v_pk_mul_f32 v[10:11], v[0:1], v[14:15] op_sel:[1,0]
	v_mov_b32_e32 v4, v54
	v_pk_fma_f32 v[8:9], v[54:55], v[8:9], v[10:11] op_sel_hi:[0,1,1] neg_lo:[0,0,1] neg_hi:[0,0,1]
	v_pk_add_f32 v[56:57], v[60:61], v[8:9]
	s_waitcnt lgkmcnt(1)
	v_mov_b32_e32 v9, v26
	v_mov_b32_e32 v26, v25
	v_mov_b32_e32 v8, v24
	v_pk_mul_f32 v[0:1], v[0:1], v[26:27] op_sel:[1,0]
	s_nop 0
	v_pk_fma_f32 v[0:1], v[54:55], v[8:9], v[0:1] op_sel_hi:[0,1,1] neg_lo:[0,0,1] neg_hi:[0,0,1]
	v_pk_add_f32 v[0:1], v[48:49], v[0:1]
	s_waitcnt lgkmcnt(0)
	v_pk_mul_f32 v[8:9], v[4:5], v[28:29]
	v_pk_mul_f32 v[4:5], v[4:5], v[30:31]
	v_mov_b32_e32 v10, v8
	v_mov_b32_e32 v11, v4
	v_mov_b32_e32 v4, v9
	v_pk_add_f32 v[4:5], v[10:11], v[4:5] neg_lo:[0,1] neg_hi:[0,1]
	ds_read_b128 v[8:11], v47 offset:768
	ds_read_b128 v[12:15], v47 offset:784
	ds_read_b128 v[24:27], v47 offset:800
	ds_read_b128 v[28:31], v47 offset:816
	v_pk_add_f32 v[4:5], v[50:51], v[4:5]
	s_waitcnt lgkmcnt(3)
	v_mov_b32_e32 v59, v10
	v_mov_b32_e32 v10, v9
	v_mov_b32_e32 v58, v8
	s_waitcnt vmcnt(0)
	v_pk_mul_f32 v[50:51], v[6:7], v[112:113] op_sel:[0,1] op_sel_hi:[0,0]
	v_pk_fma_f32 v[54:55], v[2:3], v[112:113], v[50:51] op_sel_hi:[0,1,1] neg_lo:[0,0,1] neg_hi:[0,0,1]
	v_pk_fma_f32 v[48:49], v[2:3], v[112:113], v[50:51] op_sel_hi:[0,1,1]
	v_pk_mul_f32 v[8:9], v[48:49], v[10:11] op_sel:[1,0]
	v_mov_b32_e32 v50, v54
	v_pk_fma_f32 v[8:9], v[54:55], v[58:59], v[8:9] op_sel_hi:[0,1,1] neg_lo:[0,0,1] neg_hi:[0,0,1]
	v_pk_add_f32 v[52:53], v[52:53], v[8:9]
	s_waitcnt lgkmcnt(2)
	v_mov_b32_e32 v9, v14
	v_mov_b32_e32 v14, v13
	v_mov_b32_e32 v8, v12
	v_pk_mul_f32 v[10:11], v[48:49], v[14:15] op_sel:[1,0]
	v_mov_b32_e32 v51, v49
	v_pk_fma_f32 v[8:9], v[54:55], v[8:9], v[10:11] op_sel_hi:[0,1,1] neg_lo:[0,0,1] neg_hi:[0,0,1]
	v_pk_add_f32 v[56:57], v[56:57], v[8:9]
	s_waitcnt lgkmcnt(1)
	v_mov_b32_e32 v9, v26
	v_mov_b32_e32 v26, v25
	v_mov_b32_e32 v8, v24
	v_pk_mul_f32 v[10:11], v[48:49], v[26:27] op_sel:[1,0]
	v_mov_b32_e32 v6, v7
	v_pk_fma_f32 v[8:9], v[54:55], v[8:9], v[10:11] op_sel_hi:[0,1,1] neg_lo:[0,0,1] neg_hi:[0,0,1]
	v_pk_add_f32 v[0:1], v[0:1], v[8:9]
	s_waitcnt lgkmcnt(0)
	v_pk_mul_f32 v[8:9], v[50:51], v[28:29]
	v_pk_mul_f32 v[10:11], v[50:51], v[30:31]
	v_mov_b32_e32 v12, v8
	v_mov_b32_e32 v13, v10
	v_mov_b32_e32 v10, v9
	v_pk_add_f32 v[8:9], v[12:13], v[10:11] neg_lo:[0,1] neg_hi:[0,1]
	v_mov_b32_e32 v2, v3
	v_pk_add_f32 v[4:5], v[4:5], v[8:9]
	ds_read_b128 v[8:11], v47 offset:896
	ds_read_b128 v[12:15], v47 offset:912
	ds_read_b128 v[24:27], v47 offset:928
	ds_read_b128 v[48:51], v47 offset:944
	v_add_u32_e32 v47, 0x400, v47
	v_lshl_add_u64 v[36:37], v[36:37], 0, s[30:31]
	s_waitcnt vmcnt(0)
	v_pk_mul_f32 v[6:7], v[6:7], v[114:115] op_sel:[0,1] op_sel_hi:[0,0]
	v_pk_fma_f32 v[54:55], v[2:3], v[114:115], v[6:7] op_sel_hi:[0,1,1] neg_lo:[0,0,1] neg_hi:[0,0,1]
	v_pk_fma_f32 v[2:3], v[2:3], v[114:115], v[6:7] op_sel_hi:[0,1,1]
	s_waitcnt lgkmcnt(3)
	v_mov_b32_e32 v29, v10
	v_mov_b32_e32 v10, v9
	v_mov_b32_e32 v28, v8
	v_pk_mul_f32 v[8:9], v[2:3], v[10:11] op_sel:[1,0]
	v_mov_b32_e32 v7, v3
	v_pk_fma_f32 v[8:9], v[54:55], v[28:29], v[8:9] op_sel_hi:[0,1,1] neg_lo:[0,0,1] neg_hi:[0,0,1]
	v_pk_add_f32 v[30:31], v[52:53], v[8:9]
	s_waitcnt lgkmcnt(2)
	v_mov_b32_e32 v9, v14
	v_mov_b32_e32 v14, v13
	v_mov_b32_e32 v8, v12
	v_pk_mul_f32 v[10:11], v[2:3], v[14:15] op_sel:[1,0]
	v_mov_b32_e32 v6, v54
	v_pk_fma_f32 v[8:9], v[54:55], v[8:9], v[10:11] op_sel_hi:[0,1,1] neg_lo:[0,0,1] neg_hi:[0,0,1]
	v_pk_add_f32 v[28:29], v[56:57], v[8:9]
	s_waitcnt lgkmcnt(1)
	v_mov_b32_e32 v9, v26
	v_mov_b32_e32 v26, v25
	v_mov_b32_e32 v8, v24
	v_pk_mul_f32 v[2:3], v[2:3], v[26:27] op_sel:[1,0]
	s_nop 0
	v_pk_fma_f32 v[2:3], v[54:55], v[8:9], v[2:3] op_sel_hi:[0,1,1] neg_lo:[0,0,1] neg_hi:[0,0,1]
	v_pk_add_f32 v[26:27], v[0:1], v[2:3]
	s_waitcnt lgkmcnt(0)
	v_pk_mul_f32 v[0:1], v[6:7], v[48:49]
	v_pk_mul_f32 v[2:3], v[6:7], v[50:51]
	v_mov_b32_e32 v6, v0
	v_mov_b32_e32 v7, v2
	v_mov_b32_e32 v2, v1
	v_pk_add_f32 v[0:1], v[6:7], v[2:3] neg_lo:[0,1] neg_hi:[0,1]
	s_nop 0
	v_pk_add_f32 v[24:25], v[4:5], v[0:1]
	s_cbranch_scc1 .LBB0_287
	v_readlane_b32 s50, v251, 3
	v_readlane_b32 s51, v251, 4

; __device__ __forceinline__ void ssm_kt_task(unsigned char* ws, LAS unsigned char* lds, int l, int task, int tid) {
;     ...
;         const float* cr_ = cre + (g * NP + p) * NS; const float* ci_ = cim + (g * NP + p) * NS; const f32x2* bb = bbar + (size_t)((g * 2 + dir) * NS) * NP + q;
; #pragma unroll 8
;         for (int n = 0; n < NS; ++n) { const float cr = cr_[n], ci = ci_[n]; const f32x2 b = bb[n * NP];
;             const float xr = cr * b.x - ci * b.y, xi = cr * b.y + ci * b.x;
; #pragma unroll
;             for (int s = 0; s < 8; ++s) { const f32x2 pw = Pl[(dir * 64 + n) * 16 + half * 8 + s]; acc[s] += xr * pw.x - xi * pw.y; } }
.LBB0_291:
	v_lshl_add_u64 v[4:5], v[32:33], 0, s[44:45]
	v_add_co_u32_e32 v2, vcc, 0xe400000, v4
	v_lshl_add_u64 v[0:1], v[4:5], 0, s[28:29]
	s_nop 0
	v_addc_co_u32_e32 v3, vcc, 0, v5, vcc
	v_lshl_add_u64 v[6:7], v[4:5], 0, s[26:27]
	v_add_co_u32_e32 v4, vcc, 0xe480000, v4
	global_load_dwordx4 v[8:11], v[2:3], off
	s_nop 0
	global_load_dwordx4 v[0:3], v[0:1], off offset:16
	v_addc_co_u32_e32 v5, vcc, 0, v5, vcc
	global_load_dwordx4 v[12:15], v[4:5], off
	s_nop 0
	global_load_dwordx4 v[4:7], v[6:7], off offset:16
	s_nop 0
	global_load_dwordx2 v[100:101], v[34:35], off offset:-512
	global_load_dwordx2 v[102:103], v[34:35], off offset:-384
	global_load_dwordx2 v[104:105], v[34:35], off offset:-256
	global_load_dwordx2 v[106:107], v[34:35], off offset:-128
	global_load_dwordx2 v[108:109], v[34:35], off
	global_load_dwordx2 v[110:111], v[34:35], off offset:128
	global_load_dwordx2 v[112:113], v[34:35], off offset:256
	global_load_dwordx2 v[114:115], v[34:35], off offset:384
	ds_read_b128 v[48:51], v36
	ds_read_b128 v[52:55], v36 offset:16
	ds_read_b128 v[56:59], v36 offset:32
	ds_read_b128 v[60:63], v36 offset:48
	s_add_u32 s44, s44, 32
	s_waitcnt lgkmcnt(3)
	v_mov_b32_e32 v71, v50
	v_mov_b32_e32 v50, v49
	v_mov_b32_e32 v70, v48
	s_addc_u32 s45, s45, 0
	s_cmpk_lg_i32 s44, 0x100
	s_waitcnt vmcnt(0)
	v_pk_mul_f32 v[66:67], v[12:13], v[100:101] op_sel:[0,1] op_sel_hi:[0,0]
	v_pk_fma_f32 v[68:69], v[8:9], v[100:101], v[66:67] op_sel_hi:[0,1,1] neg_lo:[0,0,1] neg_hi:[0,0,1]
	v_pk_fma_f32 v[64:65], v[8:9], v[100:101], v[66:67] op_sel_hi:[0,1,1]
	v_pk_mul_f32 v[48:49], v[64:65], v[50:51] op_sel:[1,0]
	v_mov_b32_e32 v66, v68
	v_pk_fma_f32 v[48:49], v[68:69], v[70:71], v[48:49] op_sel_hi:[0,1,1] neg_lo:[0,0,1] neg_hi:[0,0,1]
	v_pk_add_f32 v[70:71], v[30:31], v[48:49]
	s_waitcnt lgkmcnt(2)
	v_mov_b32_e32 v31, v54
	v_mov_b32_e32 v54, v53
	v_mov_b32_e32 v30, v52
	v_pk_mul_f32 v[48:49], v[64:65], v[54:55] op_sel:[1,0]
	v_mov_b32_e32 v67, v65
	v_pk_fma_f32 v[30:31], v[68:69], v[30:31], v[48:49] op_sel_hi:[0,1,1] neg_lo:[0,0,1] neg_hi:[0,0,1]
	v_pk_add_f32 v[72:73], v[28:29], v[30:31]
	s_waitcnt lgkmcnt(1)
	v_mov_b32_e32 v29, v58
	v_mov_b32_e32 v58, v57
	v_mov_b32_e32 v28, v56
	v_pk_mul_f32 v[30:31], v[64:65], v[58:59] op_sel:[1,0]
	s_nop 0
	v_pk_fma_f32 v[28:29], v[68:69], v[28:29], v[30:31] op_sel_hi:[0,1,1] neg_lo:[0,0,1] neg_hi:[0,0,1]
	v_pk_add_f32 v[56:57], v[26:27], v[28:29]
	s_waitcnt lgkmcnt(0)
	v_pk_mul_f32 v[26:27], v[66:67], v[60:61]
	v_pk_mul_f32 v[28:29], v[66:67], v[62:63]
	v_mov_b32_e32 v30, v26
	v_mov_b32_e32 v31, v28
	v_mov_b32_e32 v28, v27
	v_pk_add_f32 v[26:27], v[30:31], v[28:29] neg_lo:[0,1] neg_hi:[0,1]
	s_waitcnt vmcnt(0)
	v_pk_mul_f32 v[12:13], v[12:13], v[102:103] op_sel:[1,1] op_sel_hi:[1,0]
	v_pk_add_f32 v[58:59], v[24:25], v[26:27]
	ds_read_b128 v[24:27], v36 offset:128
	ds_read_b128 v[28:31], v36 offset:144
	ds_read_b128 v[48:51], v36 offset:160
	ds_read_b128 v[52:55], v36 offset:176
	v_pk_fma_f32 v[62:63], v[8:9], v[102:103], v[12:13] op_sel:[1,0,0] neg_lo:[0,0,1] neg_hi:[0,0,1]
	v_pk_fma_f32 v[8:9], v[8:9], v[102:103], v[12:13] op_sel:[1,0,0]
	s_waitcnt lgkmcnt(3)
	v_mov_b32_e32 v61, v26
	v_mov_b32_e32 v26, v25
	v_mov_b32_e32 v60, v24
	v_pk_mul_f32 v[24:25], v[8:9], v[26:27] op_sel:[1,0]
	v_mov_b32_e32 v13, v9
	v_pk_fma_f32 v[24:25], v[62:63], v[60:61], v[24:25] op_sel_hi:[0,1,1] neg_lo:[0,0,1] neg_hi:[0,0,1]
	v_pk_add_f32 v[60:61], v[70:71], v[24:25]
	s_waitcnt lgkmcnt(2)
	v_mov_b32_e32 v25, v30
	v_mov_b32_e32 v30, v29
	v_mov_b32_e32 v24, v28
	v_pk_mul_f32 v[26:27], v[8:9], v[30:31] op_sel:[1,0]
	v_mov_b32_e32 v12, v62
	v_pk_fma_f32 v[24:25], v[62:63], v[24:25], v[26:27] op_sel_hi:[0,1,1] neg_lo:[0,0,1] neg_hi:[0,0,1]
	v_pk_add_f32 v[64:65], v[72:73], v[24:25]
	s_waitcnt lgkmcnt(1)
	v_mov_b32_e32 v25, v50
	v_mov_b32_e32 v50, v49
	v_mov_b32_e32 v24, v48
	v_pk_mul_f32 v[8:9], v[8:9], v[50:51] op_sel:[1,0]
	s_nop 0
	v_pk_fma_f32 v[8:9], v[62:63], v[24:25], v[8:9] op_sel_hi:[0,1,1] neg_lo:[0,0,1] neg_hi:[0,0,1]
	v_pk_add_f32 v[8:9], v[56:57], v[8:9]
	s_waitcnt lgkmcnt(0)
	v_pk_mul_f32 v[24:25], v[12:13], v[52:53]
	v_pk_mul_f32 v[12:13], v[12:13], v[54:55]
	v_mov_b32_e32 v26, v24
	v_mov_b32_e32 v27, v12
	v_mov_b32_e32 v12, v25
	v_pk_add_f32 v[12:13], v[26:27], v[12:13] neg_lo:[0,1] neg_hi:[0,1]
	ds_read_b128 v[24:27], v36 offset:256
	ds_read_b128 v[28:31], v36 offset:272
	ds_read_b128 v[48:51], v36 offset:288
	ds_read_b128 v[52:55], v36 offset:304
	v_pk_add_f32 v[12:13], v[58:59], v[12:13]
	s_waitcnt lgkmcnt(3)
	v_mov_b32_e32 v67, v26
	v_mov_b32_e32 v26, v25
	v_mov_b32_e32 v66, v24
	s_waitcnt vmcnt(0)
	v_pk_mul_f32 v[58:59], v[14:15], v[104:105] op_sel:[0,1] op_sel_hi:[0,0]
	v_pk_fma_f32 v[62:63], v[10:11], v[104:105], v[58:59] op_sel_hi:[0,1,1] neg_lo:[0,0,1] neg_hi:[0,0,1]
	v_pk_fma_f32 v[56:57], v[10:11], v[104:105], v[58:59] op_sel_hi:[0,1,1]
	v_pk_mul_f32 v[24:25], v[56:57], v[26:27] op_sel:[1,0]
	v_mov_b32_e32 v59, v57
	v_pk_fma_f32 v[24:25], v[62:63], v[66:67], v[24:25] op_sel_hi:[0,1,1] neg_lo:[0,0,1] neg_hi:[0,0,1]
	v_pk_add_f32 v[60:61], v[60:61], v[24:25]
	s_waitcnt lgkmcnt(2)
	v_mov_b32_e32 v25, v30
	v_mov_b32_e32 v30, v29
	v_mov_b32_e32 v24, v28
	v_pk_mul_f32 v[26:27], v[56:57], v[30:31] op_sel:[1,0]
	v_mov_b32_e32 v58, v62
	v_pk_fma_f32 v[24:25], v[62:63], v[24:25], v[26:27] op_sel_hi:[0,1,1] neg_lo:[0,0,1] neg_hi:[0,0,1]
	v_pk_add_f32 v[64:65], v[64:65], v[24:25]
	s_waitcnt lgkmcnt(1)
	v_mov_b32_e32 v25, v50
	v_mov_b32_e32 v50, v49
	v_pk_mul_f32 v[26:27], v[56:57], v[50:51] op_sel:[1,0]
	v_mov_b32_e32 v24, v48
	v_pk_fma_f32 v[24:25], v[62:63], v[24:25], v[26:27] op_sel_hi:[0,1,1] neg_lo:[0,0,1] neg_hi:[0,0,1]
	v_pk_add_f32 v[8:9], v[8:9], v[24:25]
	s_waitcnt lgkmcnt(0)
; __device__ __forceinline__ void ssm_kt_task(unsigned char* ws, LAS unsigned char* lds, int l, int task, int tid) {
;     ...
;         const float* cr_ = cre + (g * NP + p) * NS; const float* ci_ = cim + (g * NP + p) * NS; const f32x2* bb = bbar + (size_t)((g * 2 + dir) * NS) * NP + q;
; #pragma unroll 8
;         for (int n = 0; n < NS; ++n) { const float cr = cr_[n], ci = ci_[n]; const f32x2 b = bb[n * NP];
;             const float xr = cr * b.x - ci * b.y, xi = cr * b.y + ci * b.x;
; #pragma unroll
;             for (int s = 0; s < 8; ++s) { const f32x2 pw = Pl[(dir * 64 + n) * 16 + half * 8 + s]; acc[s] += xr * pw.x - xi * pw.y; } }
	v_pk_mul_f32 v[24:25], v[58:59], v[52:53]
	v_pk_mul_f32 v[26:27], v[58:59], v[54:55]
	v_mov_b32_e32 v28, v24
	v_mov_b32_e32 v29, v26
	v_mov_b32_e32 v26, v25
	v_pk_add_f32 v[24:25], v[28:29], v[26:27] neg_lo:[0,1] neg_hi:[0,1]
	v_mov_b32_e32 v14, v15
	v_pk_add_f32 v[12:13], v[12:13], v[24:25]
	ds_read_b128 v[24:27], v36 offset:384
	ds_read_b128 v[28:31], v36 offset:400
	ds_read_b128 v[48:51], v36 offset:416
	ds_read_b128 v[52:55], v36 offset:432
	v_mov_b32_e32 v10, v11
	s_waitcnt vmcnt(0)
	v_pk_mul_f32 v[14:15], v[14:15], v[106:107] op_sel:[0,1] op_sel_hi:[0,0]
	v_pk_fma_f32 v[58:59], v[10:11], v[106:107], v[14:15] op_sel_hi:[0,1,1] neg_lo:[0,0,1] neg_hi:[0,0,1]
	v_pk_fma_f32 v[10:11], v[10:11], v[106:107], v[14:15] op_sel_hi:[0,1,1]
	s_waitcnt lgkmcnt(3)
	v_mov_b32_e32 v57, v26
	v_mov_b32_e32 v26, v25
	v_mov_b32_e32 v56, v24
	v_pk_mul_f32 v[24:25], v[10:11], v[26:27] op_sel:[1,0]
	v_mov_b32_e32 v15, v11
	v_pk_fma_f32 v[24:25], v[58:59], v[56:57], v[24:25] op_sel_hi:[0,1,1] neg_lo:[0,0,1] neg_hi:[0,0,1]
	v_pk_add_f32 v[56:57], v[60:61], v[24:25]
	s_waitcnt lgkmcnt(2)
	v_mov_b32_e32 v25, v30
	v_mov_b32_e32 v30, v29
	v_mov_b32_e32 v24, v28
	v_pk_mul_f32 v[26:27], v[10:11], v[30:31] op_sel:[1,0]
	v_mov_b32_e32 v14, v58
	v_pk_fma_f32 v[24:25], v[58:59], v[24:25], v[26:27] op_sel_hi:[0,1,1] neg_lo:[0,0,1] neg_hi:[0,0,1]
	v_pk_add_f32 v[60:61], v[64:65], v[24:25]
	s_waitcnt lgkmcnt(1)
	v_mov_b32_e32 v25, v50
	v_mov_b32_e32 v50, v49
	v_mov_b32_e32 v24, v48
	v_pk_mul_f32 v[10:11], v[10:11], v[50:51] op_sel:[1,0]
	s_nop 0
	v_pk_fma_f32 v[10:11], v[58:59], v[24:25], v[10:11] op_sel_hi:[0,1,1] neg_lo:[0,0,1] neg_hi:[0,0,1]
	v_pk_add_f32 v[48:49], v[8:9], v[10:11]
	s_waitcnt lgkmcnt(0)
	v_pk_mul_f32 v[8:9], v[14:15], v[52:53]
	v_pk_mul_f32 v[10:11], v[14:15], v[54:55]
	v_mov_b32_e32 v14, v8
	v_mov_b32_e32 v15, v10
	v_mov_b32_e32 v10, v9
	v_pk_add_f32 v[8:9], v[14:15], v[10:11] neg_lo:[0,1] neg_hi:[0,1]
	s_waitcnt vmcnt(0)
	v_pk_mul_f32 v[54:55], v[4:5], v[108:109] op_sel:[0,1] op_sel_hi:[0,0]
	v_pk_add_f32 v[50:51], v[12:13], v[8:9]
	ds_read_b128 v[8:11], v36 offset:512
	ds_read_b128 v[12:15], v36 offset:528
	ds_read_b128 v[24:27], v36 offset:544
	ds_read_b128 v[28:31], v36 offset:560
	v_pk_fma_f32 v[58:59], v[0:1], v[108:109], v[54:55] op_sel_hi:[0,1,1] neg_lo:[0,0,1] neg_hi:[0,0,1]
	v_pk_fma_f32 v[52:53], v[0:1], v[108:109], v[54:55] op_sel_hi:[0,1,1]
	s_waitcnt lgkmcnt(3)
	v_mov_b32_e32 v63, v10
	v_mov_b32_e32 v10, v9
	v_mov_b32_e32 v62, v8
	v_pk_mul_f32 v[8:9], v[52:53], v[10:11] op_sel:[1,0]
	v_mov_b32_e32 v55, v53
	v_pk_fma_f32 v[8:9], v[58:59], v[62:63], v[8:9] op_sel_hi:[0,1,1] neg_lo:[0,0,1] neg_hi:[0,0,1]
	v_pk_add_f32 v[56:57], v[56:57], v[8:9]
	s_waitcnt lgkmcnt(2)
	v_mov_b32_e32 v9, v14
	v_mov_b32_e32 v14, v13
	v_mov_b32_e32 v8, v12
	v_pk_mul_f32 v[10:11], v[52:53], v[14:15] op_sel:[1,0]
	v_mov_b32_e32 v54, v58
	v_pk_fma_f32 v[8:9], v[58:59], v[8:9], v[10:11] op_sel_hi:[0,1,1] neg_lo:[0,0,1] neg_hi:[0,0,1]
	v_pk_add_f32 v[60:61], v[60:61], v[8:9]
	s_waitcnt lgkmcnt(1)
	v_mov_b32_e32 v9, v26
	v_mov_b32_e32 v26, v25
	v_pk_mul_f32 v[10:11], v[52:53], v[26:27] op_sel:[1,0]
	v_mov_b32_e32 v8, v24
	v_pk_fma_f32 v[8:9], v[58:59], v[8:9], v[10:11] op_sel_hi:[0,1,1] neg_lo:[0,0,1] neg_hi:[0,0,1]
	v_pk_add_f32 v[48:49], v[48:49], v[8:9]
	s_waitcnt lgkmcnt(0)
	v_pk_mul_f32 v[8:9], v[54:55], v[28:29]
	v_pk_mul_f32 v[10:11], v[54:55], v[30:31]
	v_mov_b32_e32 v12, v8
	v_mov_b32_e32 v13, v10
	v_mov_b32_e32 v10, v9
	v_pk_add_f32 v[8:9], v[12:13], v[10:11] neg_lo:[0,1] neg_hi:[0,1]
	s_waitcnt vmcnt(0)
	v_pk_mul_f32 v[4:5], v[4:5], v[110:111] op_sel:[1,1] op_sel_hi:[1,0]
	v_pk_add_f32 v[50:51], v[50:51], v[8:9]
	ds_read_b128 v[8:11], v36 offset:640
	ds_read_b128 v[12:15], v36 offset:656
	ds_read_b128 v[24:27], v36 offset:672
	ds_read_b128 v[28:31], v36 offset:688
	v_pk_fma_f32 v[54:55], v[0:1], v[110:111], v[4:5] op_sel:[1,0,0] neg_lo:[0,0,1] neg_hi:[0,0,1]
	v_pk_fma_f32 v[0:1], v[0:1], v[110:111], v[4:5] op_sel:[1,0,0]
	s_waitcnt lgkmcnt(3)
	v_mov_b32_e32 v53, v10
	v_mov_b32_e32 v10, v9
	v_mov_b32_e32 v52, v8
	v_pk_mul_f32 v[8:9], v[0:1], v[10:11] op_sel:[1,0]
	v_mov_b32_e32 v5, v1
	v_pk_fma_f32 v[8:9], v[54:55], v[52:53], v[8:9] op_sel_hi:[0,1,1] neg_lo:[0,0,1] neg_hi:[0,0,1]
	v_pk_add_f32 v[52:53], v[56:57], v[8:9]
	s_waitcnt lgkmcnt(2)
; __device__ __forceinline__ void ssm_kt_task(unsigned char* ws, LAS unsigned char* lds, int l, int task, int tid) {
;     ...
;         const float* cr_ = cre + (g * NP + p) * NS; const float* ci_ = cim + (g * NP + p) * NS; const f32x2* bb = bbar + (size_t)((g * 2 + dir) * NS) * NP + q;
; #pragma unroll 8
;         for (int n = 0; n < NS; ++n) { const float cr = cr_[n], ci = ci_[n]; const f32x2 b = bb[n * NP];
;             const float xr = cr * b.x - ci * b.y, xi = cr * b.y + ci * b.x;
; #pragma unroll
;             for (int s = 0; s < 8; ++s) { const f32x2 pw = Pl[(dir * 64 + n) * 16 + half * 8 + s]; acc[s] += xr * pw.x - xi * pw.y; } }
	v_mov_b32_e32 v9, v14
	v_mov_b32_e32 v14, v13
	v_mov_b32_e32 v8, v12
	v_pk_mul_f32 v[10:11], v[0:1], v[14:15] op_sel:[1,0]
	v_mov_b32_e32 v4, v54
	v_pk_fma_f32 v[8:9], v[54:55], v[8:9], v[10:11] op_sel_hi:[0,1,1] neg_lo:[0,0,1] neg_hi:[0,0,1]
	v_pk_add_f32 v[56:57], v[60:61], v[8:9]
	s_waitcnt lgkmcnt(1)
	v_mov_b32_e32 v9, v26
	v_mov_b32_e32 v26, v25
	v_mov_b32_e32 v8, v24
	v_pk_mul_f32 v[0:1], v[0:1], v[26:27] op_sel:[1,0]
	s_nop 0
	v_pk_fma_f32 v[0:1], v[54:55], v[8:9], v[0:1] op_sel_hi:[0,1,1] neg_lo:[0,0,1] neg_hi:[0,0,1]
	v_pk_add_f32 v[0:1], v[48:49], v[0:1]
	s_waitcnt lgkmcnt(0)
	v_pk_mul_f32 v[8:9], v[4:5], v[28:29]
	v_pk_mul_f32 v[4:5], v[4:5], v[30:31]
	v_mov_b32_e32 v10, v8
	v_mov_b32_e32 v11, v4
	v_mov_b32_e32 v4, v9
	v_pk_add_f32 v[4:5], v[10:11], v[4:5] neg_lo:[0,1] neg_hi:[0,1]
	ds_read_b128 v[8:11], v36 offset:768
	ds_read_b128 v[12:15], v36 offset:784
	ds_read_b128 v[24:27], v36 offset:800
	ds_read_b128 v[28:31], v36 offset:816
	v_pk_add_f32 v[4:5], v[50:51], v[4:5]
	s_waitcnt lgkmcnt(3)
	v_mov_b32_e32 v59, v10
	v_mov_b32_e32 v10, v9
	v_mov_b32_e32 v58, v8
	s_waitcnt vmcnt(0)
	v_pk_mul_f32 v[50:51], v[6:7], v[112:113] op_sel:[0,1] op_sel_hi:[0,0]
	v_pk_fma_f32 v[54:55], v[2:3], v[112:113], v[50:51] op_sel_hi:[0,1,1] neg_lo:[0,0,1] neg_hi:[0,0,1]
	v_pk_fma_f32 v[48:49], v[2:3], v[112:113], v[50:51] op_sel_hi:[0,1,1]
	v_pk_mul_f32 v[8:9], v[48:49], v[10:11] op_sel:[1,0]
	v_mov_b32_e32 v50, v54
	v_pk_fma_f32 v[8:9], v[54:55], v[58:59], v[8:9] op_sel_hi:[0,1,1] neg_lo:[0,0,1] neg_hi:[0,0,1]
	v_pk_add_f32 v[52:53], v[52:53], v[8:9]
	s_waitcnt lgkmcnt(2)
	v_mov_b32_e32 v9, v14
	v_mov_b32_e32 v14, v13
	v_mov_b32_e32 v8, v12
	v_pk_mul_f32 v[10:11], v[48:49], v[14:15] op_sel:[1,0]
	v_mov_b32_e32 v51, v49
	v_pk_fma_f32 v[8:9], v[54:55], v[8:9], v[10:11] op_sel_hi:[0,1,1] neg_lo:[0,0,1] neg_hi:[0,0,1]
	v_pk_add_f32 v[56:57], v[56:57], v[8:9]
	s_waitcnt lgkmcnt(1)
	v_mov_b32_e32 v9, v26
	v_mov_b32_e32 v26, v25
	v_mov_b32_e32 v8, v24
	v_pk_mul_f32 v[10:11], v[48:49], v[26:27] op_sel:[1,0]
	v_mov_b32_e32 v6, v7
	v_pk_fma_f32 v[8:9], v[54:55], v[8:9], v[10:11] op_sel_hi:[0,1,1] neg_lo:[0,0,1] neg_hi:[0,0,1]
	v_pk_add_f32 v[0:1], v[0:1], v[8:9]
	s_waitcnt lgkmcnt(0)
	v_pk_mul_f32 v[8:9], v[50:51], v[28:29]
	v_pk_mul_f32 v[10:11], v[50:51], v[30:31]
	v_mov_b32_e32 v12, v8
	v_mov_b32_e32 v13, v10
	v_mov_b32_e32 v10, v9
	v_pk_add_f32 v[8:9], v[12:13], v[10:11] neg_lo:[0,1] neg_hi:[0,1]
	v_mov_b32_e32 v2, v3
	v_pk_add_f32 v[4:5], v[4:5], v[8:9]
	ds_read_b128 v[8:11], v36 offset:896
	ds_read_b128 v[12:15], v36 offset:912
	ds_read_b128 v[24:27], v36 offset:928
	ds_read_b128 v[48:51], v36 offset:944
	v_add_u32_e32 v36, 0x400, v36
	v_lshl_add_u64 v[34:35], v[34:35], 0, s[30:31]
	s_waitcnt vmcnt(0)
	v_pk_mul_f32 v[6:7], v[6:7], v[114:115] op_sel:[0,1] op_sel_hi:[0,0]
	v_pk_fma_f32 v[54:55], v[2:3], v[114:115], v[6:7] op_sel_hi:[0,1,1] neg_lo:[0,0,1] neg_hi:[0,0,1]
	v_pk_fma_f32 v[2:3], v[2:3], v[114:115], v[6:7] op_sel_hi:[0,1,1]
	s_waitcnt lgkmcnt(3)
	v_mov_b32_e32 v29, v10
	v_mov_b32_e32 v10, v9
	v_mov_b32_e32 v28, v8
	v_pk_mul_f32 v[8:9], v[2:3], v[10:11] op_sel:[1,0]
	v_mov_b32_e32 v7, v3
	v_pk_fma_f32 v[8:9], v[54:55], v[28:29], v[8:9] op_sel_hi:[0,1,1] neg_lo:[0,0,1] neg_hi:[0,0,1]
	v_pk_add_f32 v[30:31], v[52:53], v[8:9]
	s_waitcnt lgkmcnt(2)
	v_mov_b32_e32 v9, v14
	v_mov_b32_e32 v14, v13
	v_mov_b32_e32 v8, v12
	v_pk_mul_f32 v[10:11], v[2:3], v[14:15] op_sel:[1,0]
	v_mov_b32_e32 v6, v54
	v_pk_fma_f32 v[8:9], v[54:55], v[8:9], v[10:11] op_sel_hi:[0,1,1] neg_lo:[0,0,1] neg_hi:[0,0,1]
	v_pk_add_f32 v[28:29], v[56:57], v[8:9]
	s_waitcnt lgkmcnt(1)
	v_mov_b32_e32 v9, v26
	v_mov_b32_e32 v26, v25
	v_mov_b32_e32 v8, v24
	v_pk_mul_f32 v[2:3], v[2:3], v[26:27] op_sel:[1,0]
	s_nop 0
	v_pk_fma_f32 v[2:3], v[54:55], v[8:9], v[2:3] op_sel_hi:[0,1,1] neg_lo:[0,0,1] neg_hi:[0,0,1]
	v_pk_add_f32 v[26:27], v[0:1], v[2:3]
	s_waitcnt lgkmcnt(0)
	v_pk_mul_f32 v[0:1], v[6:7], v[48:49]
	v_pk_mul_f32 v[2:3], v[6:7], v[50:51]
	v_mov_b32_e32 v6, v0
	v_mov_b32_e32 v7, v2
	v_mov_b32_e32 v2, v1
	v_pk_add_f32 v[0:1], v[6:7], v[2:3] neg_lo:[0,1] neg_hi:[0,1]
	s_nop 0
	v_pk_add_f32 v[24:25], v[4:5], v[0:1]
	s_cbranch_scc1 .LBB0_291
